# MLA loop: 6-deep LDS K-fragment ring for QK, permlane32_swap row-max, running-pointer K/V addressing, static prio for backward walkers; plus 5 pipelined gemm256 K-loops
# speedup vs baseline: 1.0171x; 1.0171x over previous
; DI int obid() { int t = blockIdx.x; asm volatile("" : "+s"(t)); return t; }
; DI void ph_mix_o(const Params& P, int g, bf16_t* smem, int part, int* s_item, int rep) {
;   const int S = g ? 4096 : 8192; const int B = g ? 16 : 8;
;   const int bid = obid();
;   const int x = bid & 7, slot = bid >> 3, nslot = gridDim.x >> 3, half = nslot >> 1;
;   const int nqt = S >> 7;
;   const int nmt = S >> 8;
;   const int nxp = (g == 0) ? 32 : 0;
;   const int nm = B * nqt, nd = (B >> 1) * nmt, tot = nm + nxp + nd;
;   const bool fwd = slot < half;
;   unsigned* word = (unsigned*)(P.ws + OFF_CNT) + (g * 2 + rep) * 8 + x;
;   for (;;) {
;     const int j = queue_take(word, fwd, tot, s_item);
.LBB0_43:
	v_readlane_b32 s12, v255, 28
	s_lshr_b32 s8, s89, 7
	s_lshr_b32 s6, s89, 8
	v_readlane_b32 s13, v255, 29
	s_and_b64 s[2:3], s[12:13], exec
	v_readlane_b32 s2, v255, 33
	s_cselect_b32 s7, 32, 0
	s_lshl_b32 s42, s8, s2
	s_and_b64 s[2:3], s[12:13], exec
	s_cselect_b32 s2, 2, 3
	s_lshl_b32 s2, s6, s2
	s_or_b32 s43, s42, s7
	s_add_i32 s48, s43, s2
	v_readlane_b32 s2, v255, 27
	s_lshl_b32 s2, s2, 4
	v_readlane_b32 s3, v253, 12
	s_add_i32 s2, s2, s3
	v_cvt_f32_u32_e32 v0, s89
	s_ashr_i32 s3, s2, 31
	s_lshl_b64 s[2:3], s[2:3], 2
	v_readlane_b32 s10, v253, 10
	v_readlane_b32 s11, v253, 11
	s_add_u32 s9, s10, s2
	s_addc_u32 s10, s11, s3
	v_div_scale_f32 v2, s[2:3], v0, v0, 1.0
	v_rcp_f32_e32 v3, v2
	s_and_b64 s[2:3], s[12:13], exec
	s_cselect_b32 s2, 5, 4
	v_writelane_b32 v255, s2, 38
	v_fma_f32 v4, -v2, v3, 1.0
	s_add_i32 s2, s6, -1
	v_fmac_f32_e32 v3, v4, v3
	v_div_scale_f32 v4, vcc, 1.0, v0, 1.0
	v_writelane_b32 v255, s2, 39
	v_mul_f32_e32 v5, v4, v3
	s_lshr_b32 s2, s89, 1
	v_fma_f32 v6, -v2, v5, v4
	v_writelane_b32 v255, s2, 40
	s_and_b64 s[2:3], s[12:13], exec
	v_fmac_f32_e32 v5, v6, v3
	s_cselect_b32 s2, 12, 11
	v_fma_f32 v2, -v2, v5, v4
	v_writelane_b32 v255, s2, 41
	s_lshl_b32 s2, s89, 7
	s_add_i32 s93, s92, -1
	s_add_i32 s29, s89, -1
	s_lshl_b32 s6, s89, 4
	s_lshr_b32 s51, s89, 5
	v_div_fmas_f32 v2, v2, v3, v5
	v_cvt_f32_u32_e32 v3, s2
	s_and_b64 s[2:3], s[12:13], exec
	s_cselect_b32 s2, 6, 5
	v_writelane_b32 v255, s2, 42
	s_add_i32 s2, s8, -1
	v_writelane_b32 v255, s2, 35
	s_add_i32 s2, s8, 0x3fff
	v_writelane_b32 v255, s2, 43
	s_mov_b32 s8, s72
	v_readlane_b32 s2, v255, 23
	v_readlane_b32 s3, v255, 24
	s_load_dword s11, s[2:3], 0x0
	s_and_b64 s[2:3], s[12:13], exec
	s_cselect_b32 s2, 13, 12
	s_and_b32 s12, s8, 7
	v_writelane_b32 v255, s2, 37
	s_ashr_i32 s2, s8, 3
	s_waitcnt lgkmcnt(0)
	s_lshr_b32 s3, s11, 4
	s_lshl_b32 s11, s12, 2
	s_add_u32 s14, s9, s11
	s_addc_u32 s15, s10, 0
	s_cmp_lt_i32 s2, s3
	s_cselect_b64 s[2:3], -1, 0
	s_cbranch_scc1 .Lmixo_noprio
	s_setprio 1
.Lmixo_noprio:
	s_mov_b64 s[44:45], s[2:3]
	s_and_b64 s[2:3], s[2:3], exec
	v_writelane_b32 v255, s14, 44
	s_cselect_b32 s49, 1, 0x10000
	s_lshl_b32 s2, s8, 7
	v_writelane_b32 v255, s15, 45
	s_and_b32 s2, s2, 0x180
	v_writelane_b32 v255, s2, 46
	s_lshl_b32 s2, s2, 6
	s_lshl_b32 s3, s12, 8
	v_readlane_b32 s10, v253, 15
	v_readlane_b32 s11, v253, 16
	s_add_u32 s2, s10, s2
	v_writelane_b32 v255, s2, 47
	s_addc_u32 s2, s11, 0
	v_rsq_f32_e32 v182, v3
	v_writelane_b32 v255, s2, 48
	s_and_b32 s2, s8, 3
	s_lshl_b32 s2, s2, 12
	v_writelane_b32 v255, s2, 49
	s_lshl_b32 s2, s42, 11
	s_sub_i32 s2, s3, s2
	v_div_fixup_f32 v250, v2, v0, 1.0
	s_mov_b32 s7, s91
	s_mov_b32 s50, s12
	v_mov_b32_e32 v183, v182
	v_writelane_b32 v255, s2, 50
	s_branch .LBB0_46

; #define MLA_GLOAD(kt_, K0, K1, K2, V0, V1) { const int k0_ = (kt_) * 64; \
;     K0 = *(const uint4*)MLA_KSRC(kr0, kq0, k0_); K1 = *(const uint4*)MLA_KSRC(kr1, kq1, k0_); K2 = *(const uint4*)MLA_KSRC(kr2, kq2, k0_); \
;     V0 = *(const uint4*)(vbase + (size_t)vr0 * S + k0_ + vq0 * 8); V1 = *(const uint4*)(vbase + (size_t)vr1 * S + k0_ + vq0 * 8); }
; DI void mla_item(const Params& P, int g, int item, bf16_t* smem) {
;     ...
;   f32x16 o[2];
; #pragma unroll
;   for (int i = 0; i < 2; i++)
; #pragma unroll
;     for (int r = 0; r < 16; r++) o[i][r] = 0.f;
;   float lsum = 0.f;
;   f32x16 negm;
; #pragma unroll
;   for (int r = 0; r < 16; r++) negm[r] = 0.f;
;   uint4 rk0, rk1, rk2, rv0, rv1, qk0, qk1, qk2, qv0, qv1;
;   const bf16_t* vbase = Vt + (size_t)(b * 8 + hh) * 64 * S;
;   const int kc0 = tid, kc1 = tid + 256, kc2 = tid + 512;
;   const int kr0 = kc0 / 12, kq0 = kc0 % 12, kr1 = kc1 / 12, kq1 = kc1 % 12, kr2 = kc2 / 12, kq2 = kc2 % 12;
;   const int vr0 = tid >> 3, vq0 = tid & 7, vr1 = (tid + 256) >> 3;
;     ...
;   const int nkt = S >> 6; const int lastk = nkt - 1;
;   __syncthreads();
;   MLA_GLOAD(0, rk0, rk1, rk2, rv0, rv1) MLA_GLOAD(1, qk0, qk1, qk2, qv0, qv1) MLA_LSTORE(0, rk0, rk1, rk2, rv0, rv1)
;   __syncthreads();
.LBB0_108:
	s_or_b64 exec, exec, s[14:15]
	global_load_dwordx4 v[128:131], v[38:39], off
	global_load_dwordx4 v[132:135], v[158:159], off offset:128
	global_load_dwordx4 v[136:139], v[160:161], off offset:128
	s_movk_i32 s3, 0xd0
	v_mul_lo_u32 v27, v152, s3
	v_lshl_add_u32 v181, v44, 4, v27
	s_waitcnt vmcnt(9)
	ds_write_b128 v181, v[2:5]
	v_mul_lo_u32 v2, v154, s3
	v_lshl_add_u32 v184, v45, 4, v2
	v_mul_lo_u32 v2, v156, s3
	v_lshl_add_u32 v185, v26, 1, v2
	v_lshlrev_b32_e32 v2, 1, v42
	v_lshrrev_b32_e32 v3, 1, v43
	v_mad_u64_u32 v[164:165], s[14:15], v32, s0, v[0:1]
	v_mad_u64_u32 v[166:167], s[14:15], v30, s0, v[0:1]
	v_and_b32_e32 v0, 19, v43
	v_and_b32_e32 v2, 8, v2
	v_and_b32_e32 v3, 4, v3
	v_lshlrev_b32_e32 v162, 3, v163
	v_or3_b32 v0, v3, v0, v2
	v_mul_u32_u24_e32 v0, 0x68, v0
	v_lshlrev_b32_e32 v2, 1, v162
	v_cmp_lt_i32_e32 vcc, v236, v237
	v_lshl_add_u32 v165, v0, 1, v2
	v_readlane_b32 s16, v253, 25
	v_cndmask_b32_e32 v0, v238, v236, vcc
	v_lshlrev_b32_e32 v167, 2, v0
	v_mul_u32_u24_e32 v0, 0x48, v42
	v_readlane_b32 s14, v253, 23
	v_lshl_add_u32 v186, v0, 1, v2
	v_mov_b32_e32 v0, v22
	v_readlane_b32 s17, v253, 26
	v_readlane_b32 s15, v253, 24
	s_waitcnt vmcnt(8)
	ds_write_b128 v184, v[6:9]
	s_waitcnt vmcnt(7)
	ds_write_b128 v185, v[10:13]
	s_waitcnt vmcnt(6)
	ds_write_b128 v164, v[18:21] offset:13312
	s_waitcnt vmcnt(5)
	ds_write_b128 v166, v[14:17] offset:13312
	v_lshl_add_u64 v[168:169], v[0:1], 1, s[16:17]
	v_lshl_add_u64 v[2:3], v[34:35], 1, s[14:15]
	v_mov_b32_e32 v0, v24
	v_mov_b32_e32 v14, v1
	v_mov_b32_e32 v15, v1
	v_lshl_add_u64 v[170:171], v[22:23], 1, v[2:3]
	v_lshl_add_u64 v[172:173], v[0:1], 1, s[16:17]
	v_lshl_add_u64 v[174:175], v[24:25], 1, v[2:3]
	v_lshl_add_u64 v[178:179], v[36:37], 1, v[2:3]
	v_mov_b32_e32 v0, v1
	v_mov_b32_e32 v2, v1
	v_mov_b32_e32 v3, v1
	v_mov_b32_e32 v4, v1
	v_mov_b32_e32 v5, v1
	v_mov_b32_e32 v6, v1
	v_mov_b32_e32 v7, v1
	v_mov_b32_e32 v8, v1
	v_mov_b32_e32 v9, v1
	v_mov_b32_e32 v10, v1
	v_mov_b32_e32 v11, v1
	v_mov_b32_e32 v12, v1
	v_mov_b32_e32 v13, v1
	v_mov_b64_e32 v[62:63], v[14:15]
	v_mov_b32_e32 v149, v151
	s_mov_b32 s37, 0
	v_lshl_add_u64 v[176:177], v[28:29], 1, s[16:17]
	v_mov_b32_e32 v32, v1
	v_mov_b32_e32 v33, v1
	v_mov_b32_e32 v34, v1
	v_mov_b32_e32 v35, v1
	v_mov_b32_e32 v36, v1
	v_mov_b32_e32 v37, v1
	v_mov_b32_e32 v38, v1
	v_mov_b32_e32 v39, v1
	v_mov_b32_e32 v40, v1
	v_mov_b32_e32 v41, v1
	v_mov_b32_e32 v42, v1
	v_mov_b32_e32 v43, v1
	v_mov_b32_e32 v44, v1
	v_mov_b32_e32 v45, v1
	v_mov_b32_e32 v46, v1
	v_mov_b32_e32 v47, v1
	v_mov_b32_e32 v16, v1
	v_mov_b32_e32 v17, v1
	v_mov_b32_e32 v18, v1
	v_mov_b32_e32 v19, v1
	v_mov_b32_e32 v20, v1
	v_mov_b32_e32 v21, v1
	v_mov_b32_e32 v22, v1
	v_mov_b32_e32 v23, v1
	v_mov_b32_e32 v24, v1
	v_mov_b32_e32 v25, v1
	v_mov_b32_e32 v26, v1
	v_mov_b32_e32 v27, v1
	v_mov_b32_e32 v28, v1
	v_mov_b32_e32 v29, v1
	v_mov_b32_e32 v30, v1
	v_mov_b32_e32 v31, v1
	v_mov_b32_e32 v187, 0
	v_mov_b64_e32 v[60:61], v[12:13]
	v_mov_b64_e32 v[58:59], v[10:11]
	v_mov_b64_e32 v[56:57], v[8:9]
	v_mov_b64_e32 v[54:55], v[6:7]
	v_mov_b64_e32 v[52:53], v[4:5]
	v_mov_b64_e32 v[50:51], v[2:3]
	v_mov_b64_e32 v[48:49], v[0:1]
	s_waitcnt lgkmcnt(0)
	s_barrier
	s_add_i32 s90, s2, 0x80
	v_lshl_add_u64 v[200:201], s[90:91], 0, v[152:153]
	v_lshl_add_u64 v[204:205], s[90:91], 0, v[154:155]
	v_lshl_add_u64 v[208:209], s[90:91], 0, v[156:157]
	v_lshlrev_b64 v[202:203], 10, v[200:201]
	v_lshlrev_b64 v[200:201], 6, v[200:201]
	v_lshlrev_b64 v[206:207], 10, v[204:205]
	v_lshlrev_b64 v[204:205], 6, v[204:205]
	v_lshlrev_b64 v[210:211], 10, v[208:209]
	v_lshlrev_b64 v[208:209], 6, v[208:209]
	v_lshl_add_u64 v[200:201], v[168:169], 0, v[200:201]
	v_lshl_add_u64 v[204:205], v[172:173], 0, v[204:205]
	v_lshl_add_u64 v[208:209], v[176:177], 0, v[208:209]
	v_lshl_add_u64 v[202:203], v[170:171], 0, v[202:203]
	v_lshl_add_u64 v[200:201], v[200:201], 0, s[20:21]
	v_lshl_add_u64 v[206:207], v[174:175], 0, v[206:207]
	v_lshl_add_u64 v[204:205], v[204:205], 0, s[20:21]
	v_lshl_add_u64 v[210:211], v[178:179], 0, v[210:211]
	v_lshl_add_u64 v[208:209], v[208:209], 0, s[20:21]
	v_cndmask_b32_e64 v225, v201, v203, s[8:9]
	v_cndmask_b32_e64 v224, v200, v202, s[8:9]
	v_cndmask_b32_e64 v227, v205, v207, s[10:11]
	v_cndmask_b32_e64 v226, v204, v206, s[10:11]
	v_cndmask_b32_e64 v229, v209, v211, s[12:13]
	v_cndmask_b32_e64 v228, v208, v210, s[12:13]
	v_mov_b32_e32 v200, 0x1000
	v_mov_b32_e32 v201, 0x10000
	v_cndmask_b32_e64 v230, v200, v201, s[8:9]
	v_cndmask_b32_e64 v232, v200, v201, s[10:11]
	v_cndmask_b32_e64 v152, v200, v201, s[12:13]
	v_mov_b32_e32 v231, 0
	v_mov_b32_e32 v233, 0
	v_mov_b32_e32 v153, 0
; #define MFMA32(a, b, c) __builtin_amdgcn_mfma_f32_32x32x16_bf16((a), (b), (c), 0, 0, 0)
; #define MLA_GLOAD(kt_, K0, K1, K2, V0, V1) { const int k0_ = (kt_) * 64; \
;     K0 = *(const uint4*)MLA_KSRC(kr0, kq0, k0_); K1 = *(const uint4*)MLA_KSRC(kr1, kq1, k0_); K2 = *(const uint4*)MLA_KSRC(kr2, kq2, k0_); \
;     V0 = *(const uint4*)(vbase + (size_t)vr0 * S + k0_ + vq0 * 8); V1 = *(const uint4*)(vbase + (size_t)vr1 * S + k0_ + vq0 * 8); }
; DI void mla_compute(const bf16_t* sK, const bf16x8 (&qf)[6], f32x16 (&o)[2], f32x16& negm, float& lsum, const bool first, int l32, int h) {
;   const bf16_t* sV = sK + 64 * KLD;
;   f32x16 s[2];
;   const int kp = (l32 & 19) | ((l32 & 4) << 1) | ((l32 & 8) >> 1);
;   {
;     bf16x8 a0 = *(const bf16x8*)(sK + kp * KLD + h * 8);
;     bf16x8 a1 = *(const bf16x8*)(sK + (32 + kp) * KLD + h * 8);
;     s[0] = MFMA32(a0, qf[0], negm); s[1] = MFMA32(a1, qf[0], negm);
;   }
; #pragma unroll
;   for (int kk = 1; kk < 6; kk++) {
;     bf16x8 a0 = *(const bf16x8*)(sK + kp * KLD + kk * 16 + h * 8);
;     bf16x8 a1 = *(const bf16x8*)(sK + (32 + kp) * KLD + kk * 16 + h * 8);
;     s[0] = MFMA32(a0, qf[kk], s[0]); s[1] = MFMA32(a1, qf[kk], s[1]);
;   }
;   float mx = -1e30f;
; #pragma unroll
;   for (int i = 0; i < 2; i++)
; #pragma unroll
;     for (int r = 0; r < 16; r++) mx = fmaxf(mx, s[i][r]);
;   mx = fmaxf(mx, __shfl_xor(mx, 32));
;   if (first || __builtin_amdgcn_ballot_w64(mx > 0.f) != 0ull) {
;     const float d = first ? mx : fmaxf(mx, 0.f);
;     const float alpha = first ? 0.f : __builtin_amdgcn_exp2f(-d);
; DI void mla_item(const Params& P, int g, int item, bf16_t* smem) {
;     ...
;   for (int kt = 0; kt < nkt; kt += 2) {
;     { const int k2 = (kt + 2 < nkt) ? kt + 2 : lastk; MLA_GLOAD(k2, rk0, rk1, rk2, rv0, rv1) }
;     mla_compute(smem, qf, o, negm, lsum, kt == 0, l32, h);
.LBB0_109:
	ds_read_b128 v[200:203], v165
	ds_read_b128 v[204:207], v165 offset:6656
	ds_read_b128 v[208:211], v165 offset:32
	ds_read_b128 v[212:215], v165 offset:6688
	ds_read_b128 v[216:219], v165 offset:64
	ds_read_b128 v[220:223], v165 offset:6720
	s_add_i32 s3, s37, 2
	s_min_u32 s14, s3, s93
	s_lshl_b32 s90, s14, 7
	v_lshl_add_u64 v[14:15], v[158:159], 0, s[90:91]
	global_load_dwordx4 v[140:143], v[14:15], off
	v_lshl_add_u64 v[14:15], v[160:161], 0, s[90:91]
	global_load_dwordx4 v[2:5], v[224:225], off
	global_load_dwordx4 v[6:9], v[226:227], off
	global_load_dwordx4 v[10:13], v[228:229], off
	global_load_dwordx4 v[144:147], v[14:15], off
	s_cmp_lt_u32 s3, s93
	s_cbranch_scc0 .Lmla_noadv_a
	v_lshl_add_u64 v[224:225], v[230:231], 0, v[224:225]
	v_lshl_add_u64 v[226:227], v[232:233], 0, v[226:227]
	v_lshl_add_u64 v[228:229], v[152:153], 0, v[228:229]
.Lmla_noadv_a:
	s_cmp_eq_u32 s37, 0
	s_cselect_b64 s[14:15], -1, 0
	s_cmp_lg_u32 s37, 0
	s_waitcnt lgkmcnt(5)
	v_mfma_f32_32x32x16_bf16 v[80:95], v[200:203], v[96:99], v[48:63]
	s_waitcnt lgkmcnt(4)
	v_mfma_f32_32x32x16_bf16 v[64:79], v[204:207], v[96:99], v[48:63]
	ds_read_b128 v[200:203], v165 offset:96
	ds_read_b128 v[204:207], v165 offset:6752
	s_waitcnt lgkmcnt(5)
	v_mfma_f32_32x32x16_bf16 v[80:95], v[208:211], v[100:103], v[80:95]
	s_waitcnt lgkmcnt(4)
	v_mfma_f32_32x32x16_bf16 v[64:79], v[212:215], v[100:103], v[64:79]
	ds_read_b128 v[208:211], v165 offset:128
	ds_read_b128 v[212:215], v165 offset:6784
	s_waitcnt lgkmcnt(5)
	v_mfma_f32_32x32x16_bf16 v[80:95], v[216:219], v[104:107], v[80:95]
	s_waitcnt lgkmcnt(4)
	v_mfma_f32_32x32x16_bf16 v[64:79], v[220:223], v[104:107], v[64:79]
	ds_read_b128 v[216:219], v165 offset:160
	ds_read_b128 v[220:223], v165 offset:6816
	s_waitcnt lgkmcnt(5)
	v_mfma_f32_32x32x16_bf16 v[80:95], v[200:203], v[108:111], v[80:95]
	s_waitcnt lgkmcnt(4)
	v_mfma_f32_32x32x16_bf16 v[64:79], v[204:207], v[108:111], v[64:79]
	s_waitcnt lgkmcnt(3)
	v_mfma_f32_32x32x16_bf16 v[80:95], v[208:211], v[112:115], v[80:95]
	s_waitcnt lgkmcnt(2)
	v_mfma_f32_32x32x16_bf16 v[64:79], v[212:215], v[112:115], v[64:79]
	s_waitcnt lgkmcnt(1)
	v_mfma_f32_32x32x16_bf16 v[80:95], v[216:219], v[116:119], v[80:95]
	s_waitcnt lgkmcnt(0)
	v_mfma_f32_32x32x16_bf16 v[64:79], v[220:223], v[116:119], v[64:79]
	s_nop 9
	v_max3_f32 v0, v80, s34, v81
	v_max3_f32 v0, v0, v82, v83
	v_max3_f32 v0, v0, v84, v85
	v_max3_f32 v0, v0, v86, v87
	v_max3_f32 v0, v0, v88, v89
	v_max3_f32 v0, v0, v90, v91
	v_max3_f32 v0, v0, v92, v93
	v_max3_f32 v0, v0, v94, v95
	v_max3_f32 v0, v0, v64, v65
	v_max3_f32 v0, v0, v66, v67
	v_max3_f32 v0, v0, v68, v69
	v_max3_f32 v0, v0, v70, v71
	v_max3_f32 v0, v0, v72, v73
	v_max3_f32 v0, v0, v74, v75
	v_max3_f32 v0, v0, v76, v77
	v_max3_f32 v0, v0, v78, v79
	v_mov_b32_e32 v14, v0
	s_nop 1
	v_permlane32_swap_b32_e32 v14, v0
	v_max_f32_e32 v14, v0, v14
	s_cbranch_scc0 .LBB0_120
	v_cmp_lt_f32_e32 vcc, 0, v14
	s_mov_b64 s[18:19], 0
	s_mov_b64 s[16:17], 0
	s_cbranch_vccz .LBB0_112
	v_max_f32_e32 v0, v14, v14
	v_max_f32_e32 v0, 0, v0
	s_mov_b64 s[16:17], -1

; #define MFMA32(a, b, c) __builtin_amdgcn_mfma_f32_32x32x16_bf16((a), (b), (c), 0, 0, 0)
; DI unsigned pk2(float a, float b) { f32v2 v = {a, b}; return __builtin_bit_cast(unsigned, __builtin_convertvector(v, bf16v2)); }
; #define MLA_GLOAD(kt_, K0, K1, K2, V0, V1) { const int k0_ = (kt_) * 64; \
;     K0 = *(const uint4*)MLA_KSRC(kr0, kq0, k0_); K1 = *(const uint4*)MLA_KSRC(kr1, kq1, k0_); K2 = *(const uint4*)MLA_KSRC(kr2, kq2, k0_); \
;     V0 = *(const uint4*)(vbase + (size_t)vr0 * S + k0_ + vq0 * 8); V1 = *(const uint4*)(vbase + (size_t)vr1 * S + k0_ + vq0 * 8); }
; DI void mla_compute(const bf16_t* sK, const bf16x8 (&qf)[6], f32x16 (&o)[2], f32x16& negm, float& lsum, const bool first, int l32, int h) {
;     ...
;   float ps = 0.f;
; #pragma unroll
;   for (int i = 0; i < 2; i++)
; #pragma unroll
;     for (int r = 0; r < 16; r++) { float p = __builtin_amdgcn_exp2f(s[i][r]); s[i][r] = p; ps += p; }
;   lsum += ps;
; #pragma unroll
;   for (int mt2 = 0; mt2 < 2; mt2++)
; #pragma unroll
;     for (int st = 0; st < 2; st++) {
;       const uint4 pu = make_uint4(pk2(s[mt2][8 * st], s[mt2][8 * st + 1]), pk2(s[mt2][8 * st + 2], s[mt2][8 * st + 3]),
;                                   pk2(s[mt2][8 * st + 4], s[mt2][8 * st + 5]), pk2(s[mt2][8 * st + 6], s[mt2][8 * st + 7]));
;       const bf16x8 pf = __builtin_bit_cast(bf16x8, pu);
;       const int kb = mt2 * 32 + 16 * st + 8 * h;
; #pragma unroll
;       for (int dt = 0; dt < 2; dt++) {
;         const bf16x8 av = *(const bf16x8*)(sV + (dt * 32 + l32) * VLD + kb);
;         o[dt] = MFMA32(av, pf, o[dt]);
;       }
;     }
; DI void mla_item(const Params& P, int g, int item, bf16_t* smem) {
;     ...
;     MLA_LSTORE(1, qk0, qk1, qk2, qv0, qv1)
;     __syncthreads();
;     { const int k3 = (kt + 3 < nkt) ? kt + 3 : lastk; MLA_GLOAD(k3, qk0, qk1, qk2, qv0, qv1) }
.LBB0_116:
	v_exp_f32_e32 v14, v80
	v_exp_f32_e32 v15, v81
	v_exp_f32_e32 v80, v82
	v_exp_f32_e32 v81, v83
	v_exp_f32_e32 v82, v84
	v_exp_f32_e32 v83, v85
	v_exp_f32_e32 v84, v86
	v_exp_f32_e32 v85, v87
	v_exp_f32_e32 v190, v68
	v_exp_f32_e32 v191, v69
	v_exp_f32_e32 v192, v70
	v_exp_f32_e32 v193, v71
	v_exp_f32_e32 v194, v72
	v_exp_f32_e32 v195, v73
	v_exp_f32_e32 v196, v74
	v_exp_f32_e32 v197, v75
	ds_read_b128 v[68:71], v186 offset:13312
	ds_read_b128 v[72:75], v186 offset:13344
	v_exp_f32_e32 v86, v88
	v_exp_f32_e32 v87, v89
	v_exp_f32_e32 v88, v90
	v_exp_f32_e32 v89, v91
	v_exp_f32_e32 v90, v92
	v_exp_f32_e32 v91, v93
	v_exp_f32_e32 v92, v94
	v_exp_f32_e32 v93, v95
	v_exp_f32_e32 v94, v64
	v_exp_f32_e32 v95, v65
	v_exp_f32_e32 v188, v66
	v_exp_f32_e32 v189, v67
	v_cvt_pk_bf16_f32 v64, v14, v15
	v_cvt_pk_bf16_f32 v65, v80, v81
	v_cvt_pk_bf16_f32 v66, v82, v83
	v_cvt_pk_bf16_f32 v67, v84, v85
	v_exp_f32_e32 v76, v76
	v_exp_f32_e32 v77, v77
	s_waitcnt lgkmcnt(1)
	v_mfma_f32_32x32x16_bf16 v[32:47], v[68:71], v[64:67], v[32:47]
	ds_read_b128 v[68:71], v186 offset:17920
	v_exp_f32_e32 v78, v78
	v_exp_f32_e32 v79, v79
	v_add_f32_e32 v0, 0, v14
	s_add_i32 s14, s37, 3
	v_add_f32_e32 v0, v15, v0
	s_min_u32 s14, s14, s93
	s_waitcnt lgkmcnt(0)
	v_mfma_f32_32x32x16_bf16 v[16:31], v[68:71], v[64:67], v[16:31]
	ds_read_b128 v[68:71], v186 offset:17952
	v_cvt_pk_bf16_f32 v64, v86, v87
	v_cvt_pk_bf16_f32 v65, v88, v89
	v_cvt_pk_bf16_f32 v66, v90, v91
	v_cvt_pk_bf16_f32 v67, v92, v93
	v_add_f32_e32 v0, v80, v0
	s_waitcnt lgkmcnt(0)
	v_mfma_f32_32x32x16_bf16 v[16:31], v[68:71], v[64:67], v[16:31]
	ds_read_b128 v[68:71], v186 offset:13376
	v_add_f32_e32 v0, v81, v0
	v_add_f32_e32 v0, v82, v0
	v_add_f32_e32 v0, v83, v0
	v_add_f32_e32 v0, v84, v0
	v_mfma_f32_32x32x16_bf16 v[32:47], v[72:75], v[64:67], v[32:47]
	v_cvt_pk_bf16_f32 v64, v94, v95
	v_cvt_pk_bf16_f32 v65, v188, v189
	v_cvt_pk_bf16_f32 v66, v190, v191
	v_cvt_pk_bf16_f32 v67, v192, v193
	v_add_f32_e32 v0, v85, v0
	v_add_f32_e32 v0, v86, v0
	v_add_f32_e32 v0, v87, v0
	s_waitcnt lgkmcnt(0)
	v_mfma_f32_32x32x16_bf16 v[32:47], v[68:71], v[64:67], v[32:47]
	ds_read_b128 v[68:71], v186 offset:17984
	v_add_f32_e32 v0, v88, v0
	v_add_f32_e32 v0, v89, v0
	v_add_f32_e32 v0, v90, v0
	v_add_f32_e32 v0, v91, v0
	v_add_f32_e32 v0, v92, v0
	v_add_f32_e32 v0, v93, v0
	s_waitcnt lgkmcnt(0)
	v_mfma_f32_32x32x16_bf16 v[16:31], v[68:71], v[64:67], v[16:31]
	ds_read_b128 v[68:71], v186 offset:13408
	v_cvt_pk_bf16_f32 v64, v194, v195
	v_cvt_pk_bf16_f32 v65, v196, v197
	v_cvt_pk_bf16_f32 v66, v76, v77
	v_cvt_pk_bf16_f32 v67, v78, v79
	v_add_f32_e32 v0, v94, v0
	v_add_f32_e32 v0, v95, v0
	s_waitcnt lgkmcnt(0)
	v_mfma_f32_32x32x16_bf16 v[32:47], v[68:71], v[64:67], v[32:47]
	ds_read_b128 v[68:71], v186 offset:18016
	s_waitcnt vmcnt(9)
	ds_write_b128 v181, v[120:123] offset:22528
	s_waitcnt vmcnt(8)
	ds_write_b128 v184, v[124:127] offset:22528
	s_waitcnt vmcnt(7)
	ds_write_b128 v185, v[128:131] offset:22528
	s_waitcnt vmcnt(6)
	ds_write_b128 v164, v[132:135] offset:35840
	s_waitcnt vmcnt(5)
	ds_write_b128 v166, v[136:139] offset:35840
	s_waitcnt lgkmcnt(0)
	s_barrier
	ds_read_b128 v[200:203], v165 offset:22528
	ds_read_b128 v[204:207], v165 offset:29184
	ds_read_b128 v[208:211], v165 offset:22560
	ds_read_b128 v[212:215], v165 offset:29216
	ds_read_b128 v[216:219], v165 offset:22592
	ds_read_b128 v[220:223], v165 offset:29248
	v_add_f32_e32 v0, v188, v0
	v_add_f32_e32 v0, v189, v0
	v_mfma_f32_32x32x16_bf16 v[16:31], v[68:71], v[64:67], v[16:31]
	global_load_dwordx4 v[120:123], v[224:225], off
	global_load_dwordx4 v[124:127], v[226:227], off
	global_load_dwordx4 v[128:131], v[228:229], off
	s_lshl_b32 s90, s14, 7
	v_lshl_add_u64 v[14:15], v[158:159], 0, s[90:91]
	v_add_f32_e32 v0, v190, v0
	global_load_dwordx4 v[132:135], v[14:15], off
	v_lshl_add_u64 v[14:15], v[160:161], 0, s[90:91]
	v_add_f32_e32 v0, v191, v0
	global_load_dwordx4 v[136:139], v[14:15], off
	s_add_i32 s15, s37, 3
	s_cmp_lt_u32 s15, s93
	s_cbranch_scc0 .Lmla_noadv_b
	v_lshl_add_u64 v[224:225], v[230:231], 0, v[224:225]
	v_lshl_add_u64 v[226:227], v[232:233], 0, v[226:227]
	v_lshl_add_u64 v[228:229], v[152:153], 0, v[228:229]
; DI void mla_compute(const bf16_t* sK, const bf16x8 (&qf)[6], f32x16 (&o)[2], f32x16& negm, float& lsum, const bool first, int l32, int h) {
;     ...
;   float mx = -1e30f;
; #pragma unroll
;   for (int i = 0; i < 2; i++)
; #pragma unroll
;     for (int r = 0; r < 16; r++) mx = fmaxf(mx, s[i][r]);
;   mx = fmaxf(mx, __shfl_xor(mx, 32));
;   if (first || __builtin_amdgcn_ballot_w64(mx > 0.f) != 0ull) {
;     const float d = first ? mx : fmaxf(mx, 0.f);
;     const float alpha = first ? 0.f : __builtin_amdgcn_exp2f(-d);
; #pragma unroll
;     for (int i = 0; i < 2; i++)
; #pragma unroll
;       for (int r = 0; r < 16; r++) { s[i][r] -= d; o[i][r] *= alpha; }
; #pragma unroll
;     for (int r = 0; r < 16; r++) negm[r] -= d;
;     lsum *= alpha;
; DI void mla_item(const Params& P, int g, int item, bf16_t* smem) {
;     ...
;     mla_compute(smem + ATT_STAGE_E, qf, o, negm, lsum, false, l32, h);
.Lmla_noadv_b:
	v_add_f32_e32 v0, v192, v0
	v_add_f32_e32 v0, v193, v0
	v_add_f32_e32 v0, v194, v0
	v_add_f32_e32 v0, v195, v0
	v_add_f32_e32 v0, v196, v0
	v_add_f32_e32 v0, v197, v0
	v_add_f32_e32 v0, v76, v0
	s_waitcnt lgkmcnt(5)
	v_mfma_f32_32x32x16_bf16 v[80:95], v[200:203], v[96:99], v[48:63]
	v_add_f32_e32 v0, v77, v0
	v_add_f32_e32 v0, v78, v0
	v_add_f32_e32 v0, v79, v0
	v_add_f32_e32 v0, v187, v0
	s_waitcnt lgkmcnt(4)
	v_mfma_f32_32x32x16_bf16 v[64:79], v[204:207], v[96:99], v[48:63]
	ds_read_b128 v[200:203], v165 offset:22624
	ds_read_b128 v[204:207], v165 offset:29280
	s_waitcnt lgkmcnt(5)
	v_mfma_f32_32x32x16_bf16 v[80:95], v[208:211], v[100:103], v[80:95]
	s_waitcnt lgkmcnt(4)
	v_mfma_f32_32x32x16_bf16 v[64:79], v[212:215], v[100:103], v[64:79]
	ds_read_b128 v[208:211], v165 offset:22656
	ds_read_b128 v[212:215], v165 offset:29312
	s_waitcnt lgkmcnt(5)
	v_mfma_f32_32x32x16_bf16 v[80:95], v[216:219], v[104:107], v[80:95]
	s_waitcnt lgkmcnt(4)
	v_mfma_f32_32x32x16_bf16 v[64:79], v[220:223], v[104:107], v[64:79]
	ds_read_b128 v[216:219], v165 offset:22688
	ds_read_b128 v[220:223], v165 offset:29344
	s_waitcnt lgkmcnt(5)
	v_mfma_f32_32x32x16_bf16 v[80:95], v[200:203], v[108:111], v[80:95]
	s_waitcnt lgkmcnt(4)
	v_mfma_f32_32x32x16_bf16 v[64:79], v[204:207], v[108:111], v[64:79]
	s_waitcnt lgkmcnt(3)
	v_mfma_f32_32x32x16_bf16 v[80:95], v[208:211], v[112:115], v[80:95]
	s_waitcnt lgkmcnt(2)
	v_mfma_f32_32x32x16_bf16 v[64:79], v[212:215], v[112:115], v[64:79]
	s_waitcnt lgkmcnt(1)
	v_mfma_f32_32x32x16_bf16 v[80:95], v[216:219], v[116:119], v[80:95]
	s_waitcnt lgkmcnt(0)
	v_mfma_f32_32x32x16_bf16 v[64:79], v[220:223], v[116:119], v[64:79]
	s_nop 9
	v_max3_f32 v14, v80, s34, v81
	v_max3_f32 v14, v14, v82, v83
	v_max3_f32 v14, v14, v84, v85
	v_max3_f32 v14, v14, v86, v87
	v_max3_f32 v14, v14, v88, v89
	v_max3_f32 v14, v14, v90, v91
	v_max3_f32 v14, v14, v92, v93
	v_max3_f32 v14, v14, v94, v95
	v_max3_f32 v14, v14, v64, v65
	v_max3_f32 v14, v14, v66, v67
	v_max3_f32 v14, v14, v68, v69
	v_max3_f32 v14, v14, v70, v71
	v_max3_f32 v14, v14, v72, v73
	v_max3_f32 v14, v14, v74, v75
	v_max3_f32 v14, v14, v76, v77
	v_max3_f32 v14, v14, v78, v79
	v_mov_b32_e32 v15, v14
	s_nop 1
	v_permlane32_swap_b32_e32 v15, v14
	v_max_f32_e32 v14, v14, v15
	v_cmp_lt_f32_e32 vcc, 0, v14
	s_cbranch_vccz .LBB0_118
	v_max_f32_e32 v14, v14, v14
	v_max_f32_e32 v14, 0, v14
	v_exp_f32_e64 v188, -v14
	v_pk_add_f32 v[80:81], v[80:81], v[14:15] op_sel_hi:[1,0] neg_lo:[0,1] neg_hi:[0,1]
	v_pk_add_f32 v[82:83], v[82:83], v[14:15] op_sel_hi:[1,0] neg_lo:[0,1] neg_hi:[0,1]
	v_pk_add_f32 v[84:85], v[84:85], v[14:15] op_sel_hi:[1,0] neg_lo:[0,1] neg_hi:[0,1]
	v_pk_add_f32 v[86:87], v[86:87], v[14:15] op_sel_hi:[1,0] neg_lo:[0,1] neg_hi:[0,1]
	v_pk_add_f32 v[88:89], v[88:89], v[14:15] op_sel_hi:[1,0] neg_lo:[0,1] neg_hi:[0,1]
	v_pk_add_f32 v[90:91], v[90:91], v[14:15] op_sel_hi:[1,0] neg_lo:[0,1] neg_hi:[0,1]
	v_pk_add_f32 v[92:93], v[92:93], v[14:15] op_sel_hi:[1,0] neg_lo:[0,1] neg_hi:[0,1]
	v_pk_add_f32 v[94:95], v[94:95], v[14:15] op_sel_hi:[1,0] neg_lo:[0,1] neg_hi:[0,1]
	v_pk_add_f32 v[64:65], v[64:65], v[14:15] op_sel_hi:[1,0] neg_lo:[0,1] neg_hi:[0,1]
	v_pk_add_f32 v[66:67], v[66:67], v[14:15] op_sel_hi:[1,0] neg_lo:[0,1] neg_hi:[0,1]
	v_pk_add_f32 v[68:69], v[68:69], v[14:15] op_sel_hi:[1,0] neg_lo:[0,1] neg_hi:[0,1]
	v_pk_add_f32 v[70:71], v[70:71], v[14:15] op_sel_hi:[1,0] neg_lo:[0,1] neg_hi:[0,1]
	v_pk_add_f32 v[72:73], v[72:73], v[14:15] op_sel_hi:[1,0] neg_lo:[0,1] neg_hi:[0,1]
	v_pk_add_f32 v[74:75], v[74:75], v[14:15] op_sel_hi:[1,0] neg_lo:[0,1] neg_hi:[0,1]
	v_pk_add_f32 v[76:77], v[76:77], v[14:15] op_sel_hi:[1,0] neg_lo:[0,1] neg_hi:[0,1]
	v_pk_add_f32 v[78:79], v[78:79], v[14:15] op_sel_hi:[1,0] neg_lo:[0,1] neg_hi:[0,1]
	v_pk_mul_f32 v[30:31], v[30:31], v[188:189] op_sel_hi:[1,0]
	v_pk_mul_f32 v[28:29], v[28:29], v[188:189] op_sel_hi:[1,0]
	v_pk_mul_f32 v[26:27], v[26:27], v[188:189] op_sel_hi:[1,0]
	v_pk_mul_f32 v[24:25], v[24:25], v[188:189] op_sel_hi:[1,0]
	v_pk_mul_f32 v[22:23], v[22:23], v[188:189] op_sel_hi:[1,0]
	v_pk_mul_f32 v[20:21], v[20:21], v[188:189] op_sel_hi:[1,0]
	v_pk_mul_f32 v[18:19], v[18:19], v[188:189] op_sel_hi:[1,0]
	v_pk_mul_f32 v[16:17], v[16:17], v[188:189] op_sel_hi:[1,0]
	v_pk_mul_f32 v[46:47], v[46:47], v[188:189] op_sel_hi:[1,0]
	v_pk_mul_f32 v[44:45], v[44:45], v[188:189] op_sel_hi:[1,0]
	v_pk_mul_f32 v[42:43], v[42:43], v[188:189] op_sel_hi:[1,0]
	v_pk_mul_f32 v[40:41], v[40:41], v[188:189] op_sel_hi:[1,0]
	v_pk_mul_f32 v[38:39], v[38:39], v[188:189] op_sel_hi:[1,0]
	v_pk_mul_f32 v[36:37], v[36:37], v[188:189] op_sel_hi:[1,0]
	v_pk_mul_f32 v[34:35], v[34:35], v[188:189] op_sel_hi:[1,0]
	v_pk_mul_f32 v[32:33], v[32:33], v[188:189] op_sel_hi:[1,0]
	v_sub_f32_e32 v63, v63, v14
	v_sub_f32_e32 v62, v62, v14
	v_sub_f32_e32 v61, v61, v14
	v_sub_f32_e32 v60, v60, v14
	v_sub_f32_e32 v59, v59, v14
	v_sub_f32_e32 v58, v58, v14
	v_sub_f32_e32 v57, v57, v14
	v_sub_f32_e32 v56, v56, v14
	v_sub_f32_e32 v55, v55, v14
	v_sub_f32_e32 v54, v54, v14
	v_sub_f32_e32 v53, v53, v14
	v_sub_f32_e32 v52, v52, v14
	v_sub_f32_e32 v51, v51, v14
	v_sub_f32_e32 v50, v50, v14
	v_sub_f32_e32 v49, v49, v14
	v_sub_f32_e32 v48, v48, v14
	v_mul_f32_e32 v0, v0, v188

; DI int otid() { int t = threadIdx.x; asm volatile("" : "+v"(t)); return t; }
; DI void ph_mix_o(const Params& P, int g, bf16_t* smem, int part, int* s_item, int rep) {
;     ...
;   for (;;) {
;     const int j = queue_take(word, fwd, tot, s_item);
;     if (j < 0) break;
;     if (j < nm) {
;       if (part & 1) { const int bh = (j / nqt) * 8 + x, qt = j % nqt; mla_item(P, g, bh * nqt + qt, smem); }
;     } else if (j < nm + nxp) {
;       if (rep == 0) { const int tid0 = otid(); xprep_rows(P, 1, ((j - nm) * 8 + x) * 256, 256, tid0 >> 6, NTHR >> 6, tid0 & 63); }
;     } else {
;       if (part & 2) { const int jd = j - nm - nxp; const int pair = (jd / nmt) * 8 + x, ml = jd % nmt; dft_item(P, g, pair >> 2, ml, pair & 3, smem); }
;     }
;   }
.LBB0_128:
	s_setprio 0
	v_readlane_b32 s41, v255, 34
	v_xor_b32_e32 v240, 2, v238
	v_xor_b32_e32 v241, 1, v238
	v_mov_b32_e32 v244, 0x12000
	s_branch .LBB0_225
